# retention scan: all 12 LDS operand reads of an output tile issued up front with counted lgkmcnt (tiles 0-2)
# speedup vs baseline: 1.0045x; 1.0045x over previous
; #define LAS __attribute__((address_space(3)))
; __device__ __forceinline__ unsigned cvt_pk_bf16(float lo, float hi) { const f32x2_t v = {lo, hi}; return __builtin_bit_cast(unsigned, __builtin_convertvector(v, bf16x2_t)); }
; template <int C, int DVS, int H, bool GLA, bool PF, bool VLDS>
; __device__ void scan_phase(const bf16_t* QIN, const bf16_t* KINT, const bf16_t* ATT, const bf16_t* VT, const float* DECAY, bf16_t* O, LAS unsigned char* lds) {
;     ...
;         auto compute = [&](int n, const Frags& f) {
;             const int t0 = b * SEQ + n * C;
;             const LAS unsigned char* vb = lds + VBUF0 + (n & 1) * VBYTES + fr * VROW + 16 * fq;
; #pragma unroll
;             for (int i = 0; i < TPW; ++i) {
;                 const int ni = (TPW == 1) ? ni1 : i;
;                 f32x4 o = {0.f, 0.f, 0.f, 0.f};
; #pragma unroll
;                 for (int kk = 0; kk < KC; ++kk) {
;                     bf16x8 v;
;                     if (VLDS) v = *(const LAS bf16x8*)(vb + 16 * ni * VROW + 64 * kk);
;                     else {
;                         v = f.vf[(VLDS || TPW == 1) ? 0 : i][VLDS ? 0 : kk];
;                         if (TPW == 1) {
; #pragma unroll
;                             for (int q = 1; q < NT; ++q) v = (ni1 == q) ? f.vf[VLDS ? 0 : q][VLDS ? 0 : kk] : v;
;                         }
;                     }
;                     o = __builtin_amdgcn_mfma_f32_16x16x32_bf16(v, f.att[kk], o, 0, 0, 0);
;                 }
; #pragma unroll
;                 for (int kk = 0; kk < 8; ++kk) {
;                     const bf16x8 sb = *(const LAS bf16x8*)(lds + (n & 1) * SBYTES + ((16 * ni + fr) * SROW + 32 * kk + 8 * fq) * 2);
;                     o = __builtin_amdgcn_mfma_f32_16x16x32_bf16(sb, f.qin[kk], o, 0, 0, 0);
;                 }
;                 { u32x2 w; w.x = cvt_pk_bf16(o[0], o[1]); w.y = cvt_pk_bf16(o[2], o[3]);
;                   *(u32x2*)(O + (size_t)(t0 + 16 * ri + fr) * (H * 512) + h * 512 + sl * DVS + 16 * ni + 4 * fq) = w; }
;             }
.LBB0_234:
	s_or_b64 exec, exec, s[54:55]
	s_lshl_b64 s[52:53], s[52:53], 16
	v_lshl_add_u64 v[26:27], v[136:137], 0, s[52:53]
	global_load_dwordx4 v[126:129], v[26:27], off
	global_load_dwordx4 v[118:121], v[26:27], off offset:1024
	global_load_dwordx4 v[110:113], v[26:27], off offset:2048
	global_load_dwordx4 v[102:105], v[26:27], off offset:3072
	v_add_co_u32_e32 v26, vcc, s33, v26
	v_lshl_add_u64 v[30:31], v[138:139], 0, s[52:53]
	s_nop 0
	v_addc_co_u32_e32 v27, vcc, 0, v27, vcc
	s_and_b32 s52, s37, 1
	global_load_dwordx4 v[122:125], v[26:27], off
	global_load_dwordx4 v[114:117], v[26:27], off offset:1024
	global_load_dwordx4 v[106:109], v[26:27], off offset:2048
	global_load_dwordx4 v[98:101], v[26:27], off offset:3072
	global_load_dwordx4 v[70:73], v[30:31], off
	global_load_dwordx4 v[58:61], v[30:31], off offset:1024
	global_load_dwordx4 v[50:53], v[30:31], off offset:2048
	s_nop 0
	global_load_dwordx4 v[26:29], v[30:31], off offset:3072
	v_add_co_u32_e32 v30, vcc, s33, v30
	s_mul_i32 s53, s52, 0x4400
	s_nop 0
	v_addc_co_u32_e32 v31, vcc, 0, v31, vcc
	v_add_u32_e32 v166, s53, v158
	global_load_dwordx4 v[74:77], v[30:31], off
	global_load_dwordx4 v[62:65], v[30:31], off offset:1024
	global_load_dwordx4 v[54:57], v[30:31], off offset:2048
	s_nop 0
	global_load_dwordx4 v[30:33], v[30:31], off offset:3072
	s_mul_i32 s53, s52, 0x8400
	v_add_u32_e32 v147, s53, v159
	v_ashrrev_i32_e32 v145, 31, v144
	s_xor_b32 s52, s52, 1
	s_mul_i32 s53, s52, 0x8400
	s_andn2_b64 vcc, exec, s[38:39]
	ds_read_b128 v[180:183], v166
	ds_read_b128 v[184:187], v166 offset:64
	ds_read_b128 v[188:191], v166 offset:128
	ds_read_b128 v[192:195], v166 offset:192
	ds_read_b128 v[196:199], v147
	ds_read_b128 v[200:203], v147 offset:64
	ds_read_b128 v[204:207], v147 offset:128
	ds_read_b128 v[208:211], v147 offset:192
	ds_read_b128 v[212:215], v147 offset:256
	ds_read_b128 v[216:219], v147 offset:320
	ds_read_b128 v[172:175], v147 offset:384
	ds_read_b128 v[244:247], v147 offset:448
	s_waitcnt vmcnt(16) lgkmcnt(11)
	v_mfma_f32_16x16x32_bf16 v[82:85], v[180:183], v[78:81], 0
	s_waitcnt lgkmcnt(10)
	v_mfma_f32_16x16x32_bf16 v[82:85], v[184:187], v[66:69], v[82:85]
	s_waitcnt lgkmcnt(9)
	v_mfma_f32_16x16x32_bf16 v[82:85], v[188:191], v[94:97], v[82:85]
	s_waitcnt lgkmcnt(8)
	v_mfma_f32_16x16x32_bf16 v[82:85], v[192:195], v[90:93], v[82:85]
	s_waitcnt vmcnt(15) lgkmcnt(7)
	v_mfma_f32_16x16x32_bf16 v[82:85], v[196:199], v[126:129], v[82:85]
	s_waitcnt vmcnt(14) lgkmcnt(6)
	v_mfma_f32_16x16x32_bf16 v[82:85], v[200:203], v[118:121], v[82:85]
	s_waitcnt vmcnt(13) lgkmcnt(5)
	v_mfma_f32_16x16x32_bf16 v[82:85], v[204:207], v[110:113], v[82:85]
	s_waitcnt vmcnt(12) lgkmcnt(4)
	v_mfma_f32_16x16x32_bf16 v[82:85], v[208:211], v[102:105], v[82:85]
	s_waitcnt vmcnt(11) lgkmcnt(3)
	v_mfma_f32_16x16x32_bf16 v[82:85], v[212:215], v[122:125], v[82:85]
	s_waitcnt vmcnt(10) lgkmcnt(2)
	v_mfma_f32_16x16x32_bf16 v[82:85], v[216:219], v[114:117], v[82:85]
	s_waitcnt vmcnt(9) lgkmcnt(1)
	v_mfma_f32_16x16x32_bf16 v[82:85], v[172:175], v[106:109], v[82:85]
	s_waitcnt vmcnt(8) lgkmcnt(0)
	v_mfma_f32_16x16x32_bf16 v[82:85], v[244:247], v[98:101], v[82:85]
	ds_read_b128 v[180:183], v166 offset:4352
	ds_read_b128 v[184:187], v166 offset:4416
	ds_read_b128 v[188:191], v166 offset:4480
	ds_read_b128 v[192:195], v166 offset:4544
	ds_read_b128 v[196:199], v147 offset:8448
	ds_read_b128 v[200:203], v147 offset:8512
	ds_read_b128 v[204:207], v147 offset:8576
	ds_read_b128 v[208:211], v147 offset:8640
	ds_read_b128 v[212:215], v147 offset:8704
	ds_read_b128 v[216:219], v147 offset:8768
	ds_read_b128 v[172:175], v147 offset:8832
	ds_read_b128 v[244:247], v147 offset:8896
	v_cvt_pk_bf16_f32 v82, v82, v83
	v_cvt_pk_bf16_f32 v83, v84, v85
	v_lshlrev_b64 v[84:85], 13, v[144:145]
	v_lshl_add_u64 v[168:169], v[148:149], 0, v[84:85]
	global_store_dwordx2 v[168:169], v[82:83], off
	s_waitcnt lgkmcnt(11)
	v_mfma_f32_16x16x32_bf16 v[82:85], v[180:183], v[78:81], 0
	s_waitcnt lgkmcnt(10)
	v_mfma_f32_16x16x32_bf16 v[82:85], v[184:187], v[66:69], v[82:85]
	s_waitcnt lgkmcnt(9)
	v_mfma_f32_16x16x32_bf16 v[82:85], v[188:191], v[94:97], v[82:85]
	s_waitcnt lgkmcnt(8)
	v_mfma_f32_16x16x32_bf16 v[82:85], v[192:195], v[90:93], v[82:85]
	s_waitcnt lgkmcnt(7)
	v_mfma_f32_16x16x32_bf16 v[82:85], v[196:199], v[126:129], v[82:85]
	s_waitcnt lgkmcnt(6)
	v_mfma_f32_16x16x32_bf16 v[82:85], v[200:203], v[118:121], v[82:85]
	s_waitcnt lgkmcnt(5)
	v_mfma_f32_16x16x32_bf16 v[82:85], v[204:207], v[110:113], v[82:85]
	s_waitcnt lgkmcnt(4)
	v_mfma_f32_16x16x32_bf16 v[82:85], v[208:211], v[102:105], v[82:85]
	s_waitcnt lgkmcnt(3)
	v_mfma_f32_16x16x32_bf16 v[82:85], v[212:215], v[122:125], v[82:85]
	s_waitcnt lgkmcnt(2)
	v_mfma_f32_16x16x32_bf16 v[82:85], v[216:219], v[114:117], v[82:85]
	s_waitcnt lgkmcnt(1)
	v_mfma_f32_16x16x32_bf16 v[82:85], v[172:175], v[106:109], v[82:85]
	s_waitcnt lgkmcnt(0)
	v_mfma_f32_16x16x32_bf16 v[82:85], v[244:247], v[98:101], v[82:85]
	ds_read_b128 v[180:183], v166 offset:8704
	ds_read_b128 v[184:187], v166 offset:8768
	ds_read_b128 v[188:191], v166 offset:8832
	ds_read_b128 v[192:195], v166 offset:8896
	ds_read_b128 v[196:199], v147 offset:16896
	ds_read_b128 v[200:203], v147 offset:16960
	ds_read_b128 v[204:207], v147 offset:17024
	ds_read_b128 v[208:211], v147 offset:17088
	ds_read_b128 v[212:215], v147 offset:17152
	ds_read_b128 v[216:219], v147 offset:17216
	ds_read_b128 v[172:175], v147 offset:17280
	ds_read_b128 v[244:247], v147 offset:17344
	v_cvt_pk_bf16_f32 v82, v82, v83
	v_cvt_pk_bf16_f32 v83, v84, v85
	global_store_dwordx2 v[168:169], v[82:83], off offset:32
	s_waitcnt lgkmcnt(11)
; #define LAS __attribute__((address_space(3)))
; __device__ __forceinline__ unsigned cvt_pk_bf16(float lo, float hi) { const f32x2_t v = {lo, hi}; return __builtin_bit_cast(unsigned, __builtin_convertvector(v, bf16x2_t)); }
; template <int C, int DVS, int H, bool GLA, bool PF, bool VLDS>
; __device__ void scan_phase(const bf16_t* QIN, const bf16_t* KINT, const bf16_t* ATT, const bf16_t* VT, const float* DECAY, bf16_t* O, LAS unsigned char* lds) {
;     ...
;             for (int i = 0; i < TPW; ++i) {
;                 const int ni = (TPW == 1) ? ni1 : i;
;                 f32x4 o = {0.f, 0.f, 0.f, 0.f};
; #pragma unroll
;                 for (int kk = 0; kk < KC; ++kk) {
;                     bf16x8 v;
;                     if (VLDS) v = *(const LAS bf16x8*)(vb + 16 * ni * VROW + 64 * kk);
;                     else {
;                         v = f.vf[(VLDS || TPW == 1) ? 0 : i][VLDS ? 0 : kk];
;                         if (TPW == 1) {
; #pragma unroll
;                             for (int q = 1; q < NT; ++q) v = (ni1 == q) ? f.vf[VLDS ? 0 : q][VLDS ? 0 : kk] : v;
;                         }
;                     }
;                     o = __builtin_amdgcn_mfma_f32_16x16x32_bf16(v, f.att[kk], o, 0, 0, 0);
;                 }
; #pragma unroll
;                 for (int kk = 0; kk < 8; ++kk) {
;                     const bf16x8 sb = *(const LAS bf16x8*)(lds + (n & 1) * SBYTES + ((16 * ni + fr) * SROW + 32 * kk + 8 * fq) * 2);
;                     o = __builtin_amdgcn_mfma_f32_16x16x32_bf16(sb, f.qin[kk], o, 0, 0, 0);
;                 }
;                 { u32x2 w; w.x = cvt_pk_bf16(o[0], o[1]); w.y = cvt_pk_bf16(o[2], o[3]);
;                   *(u32x2*)(O + (size_t)(t0 + 16 * ri + fr) * (H * 512) + h * 512 + sl * DVS + 16 * ni + 4 * fq) = w; }
;             }
; #pragma unroll
;             for (int mi = 0; mi < 2; ++mi) {
;                 const f32x4 dc = GLA ? f.dec[GLA ? mi : 0] : (f32x4){dsc, dsc, dsc, dsc};
; #pragma unroll
;                 for (int ni = 0; ni < NT; ++ni) S[mi][ni] *= dc;
	v_mfma_f32_16x16x32_bf16 v[82:85], v[180:183], v[78:81], 0
	s_waitcnt lgkmcnt(10)
	v_mfma_f32_16x16x32_bf16 v[82:85], v[184:187], v[66:69], v[82:85]
	s_waitcnt lgkmcnt(9)
	v_mfma_f32_16x16x32_bf16 v[82:85], v[188:191], v[94:97], v[82:85]
	s_waitcnt lgkmcnt(8)
	v_mfma_f32_16x16x32_bf16 v[82:85], v[192:195], v[90:93], v[82:85]
	s_waitcnt lgkmcnt(7)
	v_mfma_f32_16x16x32_bf16 v[82:85], v[196:199], v[126:129], v[82:85]
	s_waitcnt lgkmcnt(6)
	v_mfma_f32_16x16x32_bf16 v[82:85], v[200:203], v[118:121], v[82:85]
	s_waitcnt lgkmcnt(5)
	v_mfma_f32_16x16x32_bf16 v[82:85], v[204:207], v[110:113], v[82:85]
	s_waitcnt lgkmcnt(4)
	v_mfma_f32_16x16x32_bf16 v[82:85], v[208:211], v[102:105], v[82:85]
	s_waitcnt lgkmcnt(3)
	v_mfma_f32_16x16x32_bf16 v[82:85], v[212:215], v[122:125], v[82:85]
	s_waitcnt lgkmcnt(2)
	v_mfma_f32_16x16x32_bf16 v[82:85], v[216:219], v[114:117], v[82:85]
	s_waitcnt lgkmcnt(1)
	v_mfma_f32_16x16x32_bf16 v[82:85], v[172:175], v[106:109], v[82:85]
	s_waitcnt lgkmcnt(0)
	v_mfma_f32_16x16x32_bf16 v[82:85], v[244:247], v[98:101], v[82:85]
	ds_read_b128 v[86:89], v166 offset:13056
	s_nop 6
	v_cvt_pk_bf16_f32 v82, v82, v83
	v_cvt_pk_bf16_f32 v83, v84, v85
	global_store_dwordx2 v[168:169], v[82:83], off offset:64
	ds_read_b128 v[82:85], v166 offset:13120
	s_waitcnt lgkmcnt(1)
	v_mfma_f32_16x16x32_bf16 v[78:81], v[86:89], v[78:81], 0
	s_waitcnt lgkmcnt(0)
	v_mfma_f32_16x16x32_bf16 v[66:69], v[82:85], v[66:69], v[78:81]
	s_nop 5
	ds_read_b128 v[78:81], v166 offset:13184
	s_waitcnt lgkmcnt(0)
	v_mfma_f32_16x16x32_bf16 v[94:97], v[78:81], v[94:97], v[66:69]
	s_nop 2
	ds_read_b128 v[66:69], v166 offset:13248
	s_waitcnt lgkmcnt(0)
	v_mfma_f32_16x16x32_bf16 v[90:93], v[66:69], v[90:93], v[94:97]
	s_nop 2
	ds_read_b128 v[94:97], v147 offset:25344
	s_waitcnt lgkmcnt(0)
	v_mfma_f32_16x16x32_bf16 v[90:93], v[94:97], v[126:129], v[90:93]
	ds_read_b128 v[94:97], v147 offset:25408
	s_waitcnt lgkmcnt(0)
	v_mfma_f32_16x16x32_bf16 v[90:93], v[94:97], v[118:121], v[90:93]
	ds_read_b128 v[94:97], v147 offset:25472
	s_waitcnt lgkmcnt(0)
	v_mfma_f32_16x16x32_bf16 v[90:93], v[94:97], v[110:113], v[90:93]
	ds_read_b128 v[94:97], v147 offset:25536
	s_waitcnt lgkmcnt(0)
	v_mfma_f32_16x16x32_bf16 v[90:93], v[94:97], v[102:105], v[90:93]
	ds_read_b128 v[94:97], v147 offset:25600
	s_waitcnt lgkmcnt(0)
	v_mfma_f32_16x16x32_bf16 v[90:93], v[94:97], v[122:125], v[90:93]
	ds_read_b128 v[94:97], v147 offset:25664
	s_waitcnt lgkmcnt(0)
	v_mfma_f32_16x16x32_bf16 v[90:93], v[94:97], v[114:117], v[90:93]
	ds_read_b128 v[94:97], v147 offset:25728
	s_waitcnt lgkmcnt(0)
	v_mfma_f32_16x16x32_bf16 v[90:93], v[94:97], v[106:109], v[90:93]
	ds_read_b128 v[94:97], v147 offset:25792
	v_mov_b32_e32 v147, v146
	s_waitcnt lgkmcnt(0)
	v_mfma_f32_16x16x32_bf16 v[90:93], v[94:97], v[98:101], v[90:93]
	v_mul_f32_e64 v96, v146, v20
	v_mul_f32_e64 v97, v147, v21
	v_pk_mul_f32 v[94:95], v[150:151], v[18:19]
	v_pk_mul_f32 v[20:21], v[146:147], v[44:45]
	s_nop 3
	v_cvt_pk_bf16_f32 v90, v90, v91
	v_cvt_pk_bf16_f32 v91, v92, v93
	global_store_dwordx2 v[168:169], v[90:91], off offset:96
	v_pk_mul_f32 v[92:93], v[146:147], v[24:25]
	v_pk_mul_f32 v[90:91], v[150:151], v[22:23]
	v_pk_mul_f32 v[24:25], v[146:147], v[48:49]
	v_pk_mul_f32 v[22:23], v[150:151], v[46:47]
	v_pk_mul_f32 v[48:49], v[146:147], v[12:13]
	v_pk_mul_f32 v[46:47], v[150:151], v[10:11]
	v_pk_mul_f32 v[12:13], v[146:147], v[36:37]
	v_pk_mul_f32 v[10:11], v[150:151], v[34:35]
	ds_read_b128 v[34:37], v166
	v_pk_mul_f32 v[18:19], v[150:151], v[42:43]
	v_pk_mul_f32 v[44:45], v[146:147], v[16:17]
	v_pk_mul_f32 v[42:43], v[150:151], v[14:15]
	v_pk_mul_f32 v[16:17], v[146:147], v[40:41]
	v_pk_mul_f32 v[14:15], v[150:151], v[38:39]
	s_waitcnt vmcnt(11) lgkmcnt(0)
	v_mfma_f32_16x16x32_bf16 v[38:41], v[70:73], v[34:37], v[94:97]
	s_waitcnt vmcnt(7)
; #define LAS __attribute__((address_space(3)))
; __device__ __forceinline__ unsigned cvt_pk_bf16(float lo, float hi) { const f32x2_t v = {lo, hi}; return __builtin_bit_cast(unsigned, __builtin_convertvector(v, bf16x2_t)); }
; template <int C, int DVS, int H, bool GLA, bool PF, bool VLDS>
; __device__ void scan_phase(const bf16_t* QIN, const bf16_t* KINT, const bf16_t* ATT, const bf16_t* VT, const float* DECAY, bf16_t* O, LAS unsigned char* lds) {
;     ...
; #pragma unroll
;             for (int kk = 0; kk < KC; ++kk)
; #pragma unroll
;                 for (int ni = 0; ni < NT; ++ni) {
;                     bf16x8 v;
;                     if (VLDS) v = *(const LAS bf16x8*)(vb + 16 * ni * VROW + 64 * kk); else v = f.vf[VLDS ? 0 : ni][VLDS ? 0 : kk];
; #pragma unroll
;                     for (int mi = 0; mi < 2; ++mi) S[mi][ni] = __builtin_amdgcn_mfma_f32_16x16x32_bf16(f.kint[mi][kk], v, S[mi][ni], 0, 0, 0);
;                 }
; #pragma unroll
;             for (int mi = 0; mi < 2; ++mi)
; #pragma unroll
;                 for (int ni = 0; ni < NT; ++ni) {
;                     u32x2 w; w.x = cvt_pk_bf16(S[mi][ni][0], S[mi][ni][1]); w.y = cvt_pk_bf16(S[mi][ni][2], S[mi][ni][3]);
;                     *(LAS u32x2*)(lds + ((n + 1) & 1) * SBYTES + ((16 * ni + fr) * SROW + 32 * wid + 16 * mi + 4 * fq) * 2) = w;
;                 }
;             if (VLDS && n + 1 < NCH) vstore((n + 1) & 1);
	v_mfma_f32_16x16x32_bf16 v[34:37], v[74:77], v[34:37], v[46:49]
	s_nop 2
	ds_read_b128 v[46:49], v166 offset:4352
	s_waitcnt lgkmcnt(0)
	v_mfma_f32_16x16x32_bf16 v[90:93], v[70:73], v[46:49], v[90:93]
	v_mfma_f32_16x16x32_bf16 v[42:45], v[74:77], v[46:49], v[42:45]
	ds_read_b128 v[46:49], v166 offset:8704
	s_waitcnt lgkmcnt(0)
	v_mfma_f32_16x16x32_bf16 v[22:25], v[70:73], v[46:49], v[22:25]
	v_mfma_f32_16x16x32_bf16 v[14:17], v[74:77], v[46:49], v[14:17]
	ds_read_b128 v[46:49], v166 offset:64
	s_waitcnt lgkmcnt(0)
	v_mfma_f32_16x16x32_bf16 v[38:41], v[58:61], v[46:49], v[38:41]
	s_waitcnt vmcnt(6)
	v_mfma_f32_16x16x32_bf16 v[34:37], v[62:65], v[46:49], v[34:37]
	ds_read_b128 v[46:49], v166 offset:4416
	v_mfma_f32_16x16x32_bf16 v[18:21], v[70:73], v[86:89], v[18:21]
	s_waitcnt lgkmcnt(0)
	v_mfma_f32_16x16x32_bf16 v[70:73], v[58:61], v[46:49], v[90:93]
	v_mfma_f32_16x16x32_bf16 v[42:45], v[62:65], v[46:49], v[42:45]
	ds_read_b128 v[46:49], v166 offset:8768
	s_waitcnt lgkmcnt(0)
	v_mfma_f32_16x16x32_bf16 v[22:25], v[58:61], v[46:49], v[22:25]
	v_mfma_f32_16x16x32_bf16 v[14:17], v[62:65], v[46:49], v[14:17]
	ds_read_b128 v[46:49], v166 offset:128
	s_waitcnt lgkmcnt(0)
	v_mfma_f32_16x16x32_bf16 v[38:41], v[50:53], v[46:49], v[38:41]
	s_waitcnt vmcnt(5)
	v_mfma_f32_16x16x32_bf16 v[34:37], v[54:57], v[46:49], v[34:37]
	ds_read_b128 v[46:49], v166 offset:4480
	v_mfma_f32_16x16x32_bf16 v[10:13], v[74:77], v[86:89], v[10:13]
	v_mfma_f32_16x16x32_bf16 v[18:21], v[58:61], v[82:85], v[18:21]
	s_waitcnt lgkmcnt(0)
	v_mfma_f32_16x16x32_bf16 v[58:61], v[50:53], v[46:49], v[70:73]
	v_mfma_f32_16x16x32_bf16 v[42:45], v[54:57], v[46:49], v[42:45]
	ds_read_b128 v[46:49], v166 offset:8832
	v_mfma_f32_16x16x32_bf16 v[10:13], v[62:65], v[82:85], v[10:13]
	s_waitcnt lgkmcnt(0)
	v_mfma_f32_16x16x32_bf16 v[70:73], v[54:57], v[46:49], v[14:17]
	v_mfma_f32_16x16x32_bf16 v[54:57], v[54:57], v[78:81], v[10:13]
	s_nop 1
	ds_read_b128 v[14:17], v166 offset:4544
	s_nop 1
	ds_read_b128 v[10:13], v166 offset:192
	v_mfma_f32_16x16x32_bf16 v[62:65], v[50:53], v[46:49], v[22:25]
	v_mfma_f32_16x16x32_bf16 v[50:53], v[50:53], v[78:81], v[18:21]
	s_waitcnt lgkmcnt(0)
	v_mfma_f32_16x16x32_bf16 v[18:21], v[26:29], v[10:13], v[38:41]
	s_waitcnt vmcnt(4)
	v_mfma_f32_16x16x32_bf16 v[10:13], v[30:33], v[10:13], v[34:37]
	s_nop 2
	ds_read_b128 v[34:37], v166 offset:8896
	v_mfma_f32_16x16x32_bf16 v[22:25], v[26:29], v[14:17], v[58:61]
	v_mfma_f32_16x16x32_bf16 v[14:17], v[30:33], v[14:17], v[42:45]
	s_waitcnt lgkmcnt(0)
	v_mfma_f32_16x16x32_bf16 v[46:49], v[26:29], v[34:37], v[62:65]
	v_mfma_f32_16x16x32_bf16 v[38:41], v[30:33], v[34:37], v[70:73]
	v_mfma_f32_16x16x32_bf16 v[42:45], v[26:29], v[66:69], v[50:53]
	v_cvt_pk_bf16_f32 v26, v18, v19
	v_cvt_pk_bf16_f32 v27, v20, v21
	s_nop 0
	v_cvt_pk_bf16_f32 v28, v22, v23
	v_mfma_f32_16x16x32_bf16 v[34:37], v[30:33], v[66:69], v[54:57]
	v_add_u32_e32 v52, s53, v160
	v_cvt_pk_bf16_f32 v50, v10, v11
	v_cvt_pk_bf16_f32 v51, v12, v13
	v_cvt_pk_bf16_f32 v29, v24, v25
	ds_write2_b64 v52, v[26:27], v[50:51] offset1:4
	v_cvt_pk_bf16_f32 v26, v14, v15
	v_cvt_pk_bf16_f32 v27, v16, v17
	v_add_u32_e32 v50, 0x2000, v52
	v_cvt_pk_bf16_f32 v30, v46, v47
	v_cvt_pk_bf16_f32 v31, v48, v49
	ds_write2_b64 v50, v[28:29], v[26:27] offset0:32 offset1:36
	v_cvt_pk_bf16_f32 v26, v38, v39
	v_cvt_pk_bf16_f32 v27, v40, v41
	v_add_u32_e32 v28, 0x4000, v52
	v_cvt_pk_bf16_f32 v32, v42, v43
	v_cvt_pk_bf16_f32 v33, v44, v45
	ds_write2_b64 v28, v[30:31], v[26:27] offset0:64 offset1:68
	v_cvt_pk_bf16_f32 v26, v34, v35
	v_cvt_pk_bf16_f32 v27, v36, v37
	v_add_u32_e32 v28, 0x6000, v52
	ds_write2_b64 v28, v[32:33], v[26:27] offset0:96 offset1:100
	s_cbranch_vccnz .LBB0_221
	s_mulk_i32 s52, 0x4400
	s_add_i32 s38, s52, 0
	s_add_i32 s38, s38, 0x10800
	v_add3_u32 v26, s38, v154, v155
	v_add3_u32 v27, s38, v156, v157
	ds_write_b128 v26, v[6:9]
	ds_write_b128 v27, v[2:5]
	s_branch .LBB0_221
